# T6 + even-layer PEER LayerNorm epilogue: gamma/beta loads pipelined 3 steps ahead with counted vmcnt (no wait on previous stores)
# speedup vs baseline: 1.0130x; 1.0017x over previous
; #define GAS __attribute__((address_space(1)))
; __device__ __forceinline__ void peer_gather_f4p(const float* X, const int* __restrict__ IDX, const float* __restrict__ G, ...
;     ...
;         asm volatile("" : "+v"(lane));
;         f32x2 xr[16];
; #pragma unroll
;         for (int j = 0; j < 8; ++j) {
;             if (RES_BF16) {
;                 const u32x2 t2 = *(const GAS u32x2*)((const GAS bf16_t*)xbout + (size_t)row * D + 256 * j + lane * 4);
;                 xr[2 * j] = f32x2{__uint_as_float(t2[0] << 16), __uint_as_float(t2[0] & 0xffff0000u)}; xr[2 * j + 1] = f32x2{__uint_as_float(t2[1] << 16), __uint_as_float(t2[1] & 0xffff0000u)};
;             } else {
;                 const f32x4 t4 = *(const GAS f32x4*)((const GAS float*)X + (size_t)row * D + 256 * j + lane * 4);
;                 xr[2 * j] = f32x2{t4[0], t4[1]}; xr[2 * j + 1] = f32x2{t4[2], t4[3]};
;             }
;         }
;         float s1 = 0.f;
; #pragma unroll
;         for (int k = 0; k < 16; ++k) { acc[k][0] = fmaf(ALPHA, xr[k][0], acc[k][0]); acc[k][1] = fmaf(ALPHA, xr[k][1], acc[k][1]); s1 += acc[k][0] + acc[k][1]; }
;         const float mu = wsum(s1) * (1.f / D);
.LBB0_548:
	s_add_i32 s16, s19, s62
	s_ashr_i32 s17, s16, 31
	s_lshl_b64 s[16:17], s[16:17], 12
	s_add_u32 s16, s15, s16
	s_waitcnt vmcnt(15)
	v_lshlrev_b32_e32 v4, 2, v2
	s_addc_u32 s17, s18, s17
	v_ashrrev_i32_e32 v5, 31, v4
	s_waitcnt vmcnt(13)
	v_lshl_add_u64 v[12:13], v[4:5], 1, s[16:17]
	global_load_dwordx2 v[20:21], v[12:13], off
	global_load_dwordx2 v[24:25], v[12:13], off offset:512
	global_load_dwordx2 v[28:29], v[12:13], off offset:1024
	global_load_dwordx2 v[32:33], v[12:13], off offset:1536
	global_load_dwordx2 v[36:37], v[12:13], off offset:2048
	global_load_dwordx2 v[40:41], v[12:13], off offset:2560
	global_load_dwordx2 v[44:45], v[12:13], off offset:3072
	global_load_dwordx2 v[48:49], v[12:13], off offset:3584
	s_mov_b64 s[16:17], s[42:43]
	s_mov_b64 s[26:27], s[44:45]
	v_lshlrev_b64 v[8:9], 2, v[4:5]
	s_addk_i32 s12, 0x200
	s_waitcnt vmcnt(20)
	v_lshl_add_u64 v[16:17], s[26:27], 0, v[8:9]
	v_lshl_add_u64 v[14:15], s[16:17], 0, v[8:9]
	global_load_dwordx4 v[4:7], v[16:17], off
	global_load_dwordx4 v[8:11], v[14:15], off
	s_movk_i32 s16, 0x1000
	s_cmp_lg_u32 s13, 4
	s_waitcnt vmcnt(9)
	v_lshlrev_b32_e32 v22, 16, v20
	v_and_b32_e32 v23, 0xffff0000, v20
	v_lshlrev_b32_e32 v18, 16, v21
	v_and_b32_e32 v19, 0xffff0000, v21
	v_pk_fma_f32 v[22:23], v[22:23], s[2:3], v[194:195] op_sel_hi:[1,0,1]
	v_pk_fma_f32 v[18:19], v[18:19], s[2:3], v[196:197] op_sel_hi:[1,0,1]
	v_add_f32_e32 v20, v23, v22
	v_add_f32_e32 v2, v19, v18
	v_add_f32_e32 v20, 0, v20
	s_waitcnt vmcnt(8)
	v_lshlrev_b32_e32 v26, 16, v24
	v_and_b32_e32 v27, 0xffff0000, v24
	v_add_f32_e32 v2, v2, v20
	v_lshlrev_b32_e32 v20, 16, v25
	v_and_b32_e32 v21, 0xffff0000, v25
	v_pk_fma_f32 v[26:27], v[26:27], s[2:3], v[190:191] op_sel_hi:[1,0,1]
	v_pk_fma_f32 v[20:21], v[20:21], s[2:3], v[192:193] op_sel_hi:[1,0,1]
	v_add_f32_e32 v24, v27, v26
	v_add_f32_e32 v25, v21, v20
	v_add_f32_e32 v2, v24, v2
	s_waitcnt vmcnt(7)
	v_lshlrev_b32_e32 v30, 16, v28
	v_and_b32_e32 v31, 0xffff0000, v28
	v_add_f32_e32 v2, v25, v2
	v_lshlrev_b32_e32 v24, 16, v29
	v_and_b32_e32 v25, 0xffff0000, v29
	v_pk_fma_f32 v[30:31], v[30:31], s[2:3], v[186:187] op_sel_hi:[1,0,1]
	v_pk_fma_f32 v[24:25], v[24:25], s[2:3], v[188:189] op_sel_hi:[1,0,1]
	v_add_f32_e32 v28, v31, v30
	v_add_f32_e32 v29, v25, v24
	v_add_f32_e32 v2, v28, v2
	s_waitcnt vmcnt(6)
	v_lshlrev_b32_e32 v34, 16, v32
	v_and_b32_e32 v35, 0xffff0000, v32
	v_add_f32_e32 v2, v29, v2
	v_lshlrev_b32_e32 v28, 16, v33
	v_and_b32_e32 v29, 0xffff0000, v33
	v_pk_fma_f32 v[34:35], v[34:35], s[2:3], v[182:183] op_sel_hi:[1,0,1]
	v_pk_fma_f32 v[28:29], v[28:29], s[2:3], v[184:185] op_sel_hi:[1,0,1]
	v_add_f32_e32 v32, v35, v34
	v_add_f32_e32 v33, v29, v28
	v_add_f32_e32 v2, v32, v2
	s_waitcnt vmcnt(5)
	v_lshlrev_b32_e32 v38, 16, v36
	v_and_b32_e32 v39, 0xffff0000, v36
	v_add_f32_e32 v2, v33, v2
	v_lshlrev_b32_e32 v32, 16, v37
	v_and_b32_e32 v33, 0xffff0000, v37
	v_pk_fma_f32 v[38:39], v[38:39], s[2:3], v[178:179] op_sel_hi:[1,0,1]
	v_pk_fma_f32 v[32:33], v[32:33], s[2:3], v[180:181] op_sel_hi:[1,0,1]
	v_add_f32_e32 v36, v39, v38
	v_add_f32_e32 v37, v33, v32
	v_add_f32_e32 v2, v36, v2
	s_waitcnt vmcnt(4)
	v_lshlrev_b32_e32 v42, 16, v40
	v_and_b32_e32 v43, 0xffff0000, v40
	v_add_f32_e32 v2, v37, v2
	v_lshlrev_b32_e32 v36, 16, v41
	v_and_b32_e32 v37, 0xffff0000, v41
	v_pk_fma_f32 v[42:43], v[42:43], s[2:3], v[174:175] op_sel_hi:[1,0,1]
	v_pk_fma_f32 v[36:37], v[36:37], s[2:3], v[176:177] op_sel_hi:[1,0,1]
	v_add_f32_e32 v40, v43, v42
	v_add_f32_e32 v41, v37, v36
	v_add_f32_e32 v2, v40, v2
	s_waitcnt vmcnt(3)
	v_lshlrev_b32_e32 v46, 16, v44
	v_and_b32_e32 v47, 0xffff0000, v44
	v_add_f32_e32 v2, v41, v2
	v_lshlrev_b32_e32 v40, 16, v45
	v_and_b32_e32 v41, 0xffff0000, v45
	v_pk_fma_f32 v[46:47], v[46:47], s[2:3], v[170:171] op_sel_hi:[1,0,1]
	v_pk_fma_f32 v[40:41], v[40:41], s[2:3], v[172:173] op_sel_hi:[1,0,1]
	v_add_f32_e32 v44, v47, v46
	v_add_f32_e32 v45, v41, v40
	v_add_f32_e32 v2, v44, v2
	s_waitcnt vmcnt(2)
	v_lshlrev_b32_e32 v50, 16, v48
	v_and_b32_e32 v51, 0xffff0000, v48
	v_add_f32_e32 v2, v45, v2
	v_lshlrev_b32_e32 v44, 16, v49
	v_and_b32_e32 v45, 0xffff0000, v49
	v_pk_fma_f32 v[48:49], v[50:51], s[2:3], v[166:167] op_sel_hi:[1,0,1]
	v_pk_fma_f32 v[44:45], v[44:45], s[2:3], v[168:169] op_sel_hi:[1,0,1]
	v_add_f32_e32 v50, v49, v48
	v_add_f32_e32 v52, v45, v44
	v_add_f32_e32 v2, v50, v2
	v_add_f32_e32 v2, v52, v2
	ds_swizzle_b32 v50, v2 offset:swizzle(SWAP,1)
	s_waitcnt lgkmcnt(0)
	v_add_f32_e32 v2, v2, v50
	ds_swizzle_b32 v50, v2 offset:swizzle(SWAP,2)
	s_waitcnt lgkmcnt(0)
	v_add_f32_e32 v2, v2, v50
	ds_swizzle_b32 v50, v2 offset:swizzle(SWAP,4)
	s_waitcnt lgkmcnt(0)
	v_add_f32_e32 v2, v2, v50
	ds_swizzle_b32 v50, v2 offset:swizzle(SWAP,8)
	s_waitcnt lgkmcnt(0)
	v_add_f32_e32 v2, v2, v50
	ds_swizzle_b32 v50, v2 offset:swizzle(SWAP,16)
	s_waitcnt lgkmcnt(0)
; #define GAS __attribute__((address_space(1)))
; __device__ __forceinline__ unsigned cvtpk(float lo, float hi) { return __builtin_bit_cast(unsigned, __builtin_convertvector(f32x2_cv{lo, hi}, bf16x2_cv)); }
; __device__ __forceinline__ void peer_gather_f4p(const float* X, const int* __restrict__ IDX, const float* __restrict__ G, ...
;     ...
;         const float mu = wsum(s1) * (1.f / D);
;         float s2 = 0.f;
; #pragma unroll
;         for (int k = 0; k < 16; ++k) { const float d0 = acc[k][0] - mu, d1 = acc[k][1] - mu; s2 = fmaf(d0, d0, s2); s2 = fmaf(d1, d1, s2); }
;         const float rstd = rsqrtf(wsum(s2) * (1.f / D) + LN_EPS);
;         const float* gl_ = g; const float* bl_ = bb;
;         asm volatile("" : "+s"(gl_), "+s"(bl_));
; #pragma unroll
;         for (int j = 0; j < 8; ++j) {
;             const int col = 256 * j + lane * 4;
;             const f32x4 g4 = *(const GAS f32x4*)((const GAS float*)gl_ + col), b4 = *(const GAS f32x4*)((const GAS float*)bl_ + col);
;             f32x4 o4;
;             o4[0] = (acc[2 * j][0] - mu) * rstd * g4[0] + b4[0]; o4[1] = (acc[2 * j][1] - mu) * rstd * g4[1] + b4[1];
;             o4[2] = (acc[2 * j + 1][0] - mu) * rstd * g4[2] + b4[2]; o4[3] = (acc[2 * j + 1][1] - mu) * rstd * g4[3] + b4[3];
;             if (!RES_BF16 || dst != nullptr) *(GAS f32x4*)((GAS float*)dst + (size_t)row * D + col) = o4;
;             *(GAS u32x2*)((GAS bf16_t*)xbout + (size_t)row * D + col) = u32x2{cvtpk(o4[0], o4[1]), cvtpk(o4[2], o4[3])};
	v_add_f32_e32 v2, v2, v50
	v_mov_b32_e32 v50, v2
	s_nop 1
	v_permlane32_swap_b32_e32 v2, v50
	v_add_f32_e32 v2, v2, v50
	v_mul_f32_e32 v2, 0x3a000000, v2
	v_pk_add_f32 v[50:51], v[22:23], v[2:3] op_sel_hi:[1,0] neg_lo:[0,1] neg_hi:[0,1]
	v_pk_add_f32 v[52:53], v[18:19], v[2:3] op_sel_hi:[1,0] neg_lo:[0,1] neg_hi:[0,1]
	v_fma_f32 v100, v50, v50, 0
	v_fmac_f32_e32 v100, v51, v51
	v_fmac_f32_e32 v100, v52, v52
	v_fmac_f32_e32 v100, v53, v53
	v_pk_add_f32 v[54:55], v[26:27], v[2:3] op_sel_hi:[1,0] neg_lo:[0,1] neg_hi:[0,1]
	v_pk_add_f32 v[58:59], v[20:21], v[2:3] op_sel_hi:[1,0] neg_lo:[0,1] neg_hi:[0,1]
	v_fmac_f32_e32 v100, v54, v54
	v_fmac_f32_e32 v100, v55, v55
	v_fmac_f32_e32 v100, v58, v58
	v_fmac_f32_e32 v100, v59, v59
	v_pk_add_f32 v[56:57], v[30:31], v[2:3] op_sel_hi:[1,0] neg_lo:[0,1] neg_hi:[0,1]
	v_pk_add_f32 v[60:61], v[24:25], v[2:3] op_sel_hi:[1,0] neg_lo:[0,1] neg_hi:[0,1]
	v_fmac_f32_e32 v100, v56, v56
	v_fmac_f32_e32 v100, v57, v57
	v_fmac_f32_e32 v100, v60, v60
	v_fmac_f32_e32 v100, v61, v61
	v_pk_add_f32 v[34:35], v[34:35], v[2:3] op_sel_hi:[1,0] neg_lo:[0,1] neg_hi:[0,1]
	v_pk_add_f32 v[62:63], v[28:29], v[2:3] op_sel_hi:[1,0] neg_lo:[0,1] neg_hi:[0,1]
	v_fmac_f32_e32 v100, v34, v34
	v_fmac_f32_e32 v100, v35, v35
	v_fmac_f32_e32 v100, v62, v62
	v_fmac_f32_e32 v100, v63, v63
	v_pk_add_f32 v[18:19], v[38:39], v[2:3] op_sel_hi:[1,0] neg_lo:[0,1] neg_hi:[0,1]
	v_pk_add_f32 v[24:25], v[32:33], v[2:3] op_sel_hi:[1,0] neg_lo:[0,1] neg_hi:[0,1]
	v_fmac_f32_e32 v100, v18, v18
	v_fmac_f32_e32 v100, v19, v19
	v_fmac_f32_e32 v100, v24, v24
	v_fmac_f32_e32 v100, v25, v25
	v_pk_add_f32 v[20:21], v[42:43], v[2:3] op_sel_hi:[1,0] neg_lo:[0,1] neg_hi:[0,1]
	v_pk_add_f32 v[28:29], v[36:37], v[2:3] op_sel_hi:[1,0] neg_lo:[0,1] neg_hi:[0,1]
	v_fmac_f32_e32 v100, v20, v20
	v_fmac_f32_e32 v100, v21, v21
	v_fmac_f32_e32 v100, v28, v28
	v_fmac_f32_e32 v100, v29, v29
	v_pk_add_f32 v[22:23], v[46:47], v[2:3] op_sel_hi:[1,0] neg_lo:[0,1] neg_hi:[0,1]
	v_pk_add_f32 v[30:31], v[40:41], v[2:3] op_sel_hi:[1,0] neg_lo:[0,1] neg_hi:[0,1]
	v_fmac_f32_e32 v100, v22, v22
	v_fmac_f32_e32 v100, v23, v23
	v_fmac_f32_e32 v100, v30, v30
	v_fmac_f32_e32 v100, v31, v31
	v_pk_add_f32 v[26:27], v[48:49], v[2:3] op_sel_hi:[1,0] neg_lo:[0,1] neg_hi:[0,1]
	v_pk_add_f32 v[32:33], v[44:45], v[2:3] op_sel_hi:[1,0] neg_lo:[0,1] neg_hi:[0,1]
	v_fmac_f32_e32 v100, v26, v26
	v_fmac_f32_e32 v100, v27, v27
	v_fmac_f32_e32 v100, v32, v32
	v_fmac_f32_e32 v100, v33, v33
	ds_swizzle_b32 v2, v100 offset:swizzle(SWAP,1)
	s_waitcnt lgkmcnt(0)
	v_add_f32_e32 v2, v100, v2
	ds_swizzle_b32 v36, v2 offset:swizzle(SWAP,2)
	s_waitcnt lgkmcnt(0)
	v_add_f32_e32 v2, v2, v36
	ds_swizzle_b32 v36, v2 offset:swizzle(SWAP,4)
	s_waitcnt lgkmcnt(0)
	v_add_f32_e32 v2, v2, v36
	ds_swizzle_b32 v36, v2 offset:swizzle(SWAP,8)
	s_waitcnt lgkmcnt(0)
	v_add_f32_e32 v2, v2, v36
	ds_swizzle_b32 v36, v2 offset:swizzle(SWAP,16)
	s_waitcnt lgkmcnt(0)
	v_add_f32_e32 v2, v2, v36
	v_mov_b32_e32 v36, v2
	s_nop 1
	v_permlane32_swap_b32_e32 v2, v36
	v_add_f32_e32 v2, v2, v36
	v_fmamk_f32 v2, v2, 0x3a000000, v200
	v_cmp_gt_f32_e32 vcc, s33, v2
	v_mul_f32_e32 v36, 0x4b800000, v2
	s_nop 0
	v_cndmask_b32_e32 v2, v2, v36, vcc
	v_rsq_f32_e32 v2, v2
	s_nop 0
	v_mul_f32_e32 v36, 0x45800000, v2
	v_cndmask_b32_e32 v2, v2, v36, vcc
	global_load_dwordx4 v[220:223], v[16:17], off offset:1024
	global_load_dwordx4 v[236:239], v[14:15], off offset:1024
	global_load_dwordx4 v[224:227], v[16:17], off offset:2048
	global_load_dwordx4 v[240:243], v[14:15], off offset:2048
	global_load_dwordx4 v[228:231], v[16:17], off offset:3072
	global_load_dwordx4 v[244:247], v[14:15], off offset:3072
	v_pk_mul_f32 v[36:37], v[50:51], v[2:3] op_sel_hi:[1,0]
	v_pk_mul_f32 v[38:39], v[52:53], v[2:3] op_sel_hi:[1,0]
	s_waitcnt vmcnt(6)
; #define GAS __attribute__((address_space(1)))
; __device__ __forceinline__ unsigned cvtpk(float lo, float hi) { return __builtin_bit_cast(unsigned, __builtin_convertvector(f32x2_cv{lo, hi}, bf16x2_cv)); }
; __device__ __forceinline__ void peer_gather_f4p(const float* X, const int* __restrict__ IDX, const float* __restrict__ G, ...
;     ...
; #pragma unroll
;         for (int j = 0; j < 8; ++j) {
;             const int col = 256 * j + lane * 4;
;             const f32x4 g4 = *(const GAS f32x4*)((const GAS float*)gl_ + col), b4 = *(const GAS f32x4*)((const GAS float*)bl_ + col);
;             f32x4 o4;
;             o4[0] = (acc[2 * j][0] - mu) * rstd * g4[0] + b4[0]; o4[1] = (acc[2 * j][1] - mu) * rstd * g4[1] + b4[1];
;             o4[2] = (acc[2 * j + 1][0] - mu) * rstd * g4[2] + b4[2]; o4[3] = (acc[2 * j + 1][1] - mu) * rstd * g4[3] + b4[3];
;             if (!RES_BF16 || dst != nullptr) *(GAS f32x4*)((GAS float*)dst + (size_t)row * D + col) = o4;
;             *(GAS u32x2*)((GAS bf16_t*)xbout + (size_t)row * D + col) = u32x2{cvtpk(o4[0], o4[1]), cvtpk(o4[2], o4[3])};
;         }
	v_pk_fma_f32 v[40:41], v[4:5], v[36:37], v[8:9]
	v_pk_fma_f32 v[42:43], v[6:7], v[38:39], v[10:11]
	v_cvt_pk_bf16_f32 v44, v40, v41
	v_cvt_pk_bf16_f32 v45, v42, v43
	global_store_dwordx2 v[12:13], v[44:45], off
	v_add_co_u32_e32 v16, vcc, s16, v16
	s_nop 1
	v_addc_co_u32_e32 v17, vcc, 0, v17, vcc
	v_add_co_u32_e32 v14, vcc, s16, v14
	s_nop 1
	v_addc_co_u32_e32 v15, vcc, 0, v15, vcc
	global_load_dwordx4 v[216:219], v[16:17], off
	global_load_dwordx4 v[232:235], v[14:15], off
	v_pk_mul_f32 v[36:37], v[54:55], v[2:3] op_sel_hi:[1,0]
	v_pk_mul_f32 v[38:39], v[58:59], v[2:3] op_sel_hi:[1,0]
	s_waitcnt vmcnt(7)
	v_pk_fma_f32 v[40:41], v[220:221], v[36:37], v[236:237]
	v_pk_fma_f32 v[42:43], v[222:223], v[38:39], v[238:239]
	v_cvt_pk_bf16_f32 v46, v40, v41
	v_cvt_pk_bf16_f32 v47, v42, v43
	global_store_dwordx2 v[12:13], v[46:47], off offset:512
	global_load_dwordx4 v[220:223], v[16:17], off offset:1024
	global_load_dwordx4 v[236:239], v[14:15], off offset:1024
	v_pk_mul_f32 v[36:37], v[56:57], v[2:3] op_sel_hi:[1,0]
	v_pk_mul_f32 v[38:39], v[60:61], v[2:3] op_sel_hi:[1,0]
	s_waitcnt vmcnt(8)
	v_pk_fma_f32 v[40:41], v[224:225], v[36:37], v[240:241]
	v_pk_fma_f32 v[42:43], v[226:227], v[38:39], v[242:243]
	v_cvt_pk_bf16_f32 v44, v40, v41
	v_cvt_pk_bf16_f32 v45, v42, v43
	global_store_dwordx2 v[12:13], v[44:45], off offset:1024
	global_load_dwordx4 v[224:227], v[16:17], off offset:2048
	global_load_dwordx4 v[240:243], v[14:15], off offset:2048
	v_pk_mul_f32 v[36:37], v[34:35], v[2:3] op_sel_hi:[1,0]
	v_pk_mul_f32 v[38:39], v[62:63], v[2:3] op_sel_hi:[1,0]
	s_waitcnt vmcnt(9)
	v_pk_fma_f32 v[40:41], v[228:229], v[36:37], v[244:245]
	v_pk_fma_f32 v[42:43], v[230:231], v[38:39], v[246:247]
	v_cvt_pk_bf16_f32 v46, v40, v41
	v_cvt_pk_bf16_f32 v47, v42, v43
	global_store_dwordx2 v[12:13], v[46:47], off offset:1536
	global_load_dwordx4 v[228:231], v[16:17], off offset:3072
	global_load_dwordx4 v[244:247], v[14:15], off offset:3072
	v_pk_mul_f32 v[36:37], v[18:19], v[2:3] op_sel_hi:[1,0]
	v_pk_mul_f32 v[38:39], v[24:25], v[2:3] op_sel_hi:[1,0]
	s_waitcnt vmcnt(9)
	v_pk_fma_f32 v[40:41], v[216:217], v[36:37], v[232:233]
	v_pk_fma_f32 v[42:43], v[218:219], v[38:39], v[234:235]
	v_cvt_pk_bf16_f32 v44, v40, v41
	v_cvt_pk_bf16_f32 v45, v42, v43
	global_store_dwordx2 v[12:13], v[44:45], off offset:2048
	v_pk_mul_f32 v[36:37], v[20:21], v[2:3] op_sel_hi:[1,0]
	v_pk_mul_f32 v[38:39], v[28:29], v[2:3] op_sel_hi:[1,0]
	s_waitcnt vmcnt(7)
	v_pk_fma_f32 v[40:41], v[220:221], v[36:37], v[236:237]
	v_pk_fma_f32 v[42:43], v[222:223], v[38:39], v[238:239]
	v_cvt_pk_bf16_f32 v46, v40, v41
	v_cvt_pk_bf16_f32 v47, v42, v43
	global_store_dwordx2 v[12:13], v[46:47], off offset:2560
	v_pk_mul_f32 v[36:37], v[22:23], v[2:3] op_sel_hi:[1,0]
	v_pk_mul_f32 v[38:39], v[30:31], v[2:3] op_sel_hi:[1,0]
	s_waitcnt vmcnt(5)
	v_pk_fma_f32 v[40:41], v[224:225], v[36:37], v[240:241]
	v_pk_fma_f32 v[42:43], v[226:227], v[38:39], v[242:243]
	v_cvt_pk_bf16_f32 v44, v40, v41
	v_cvt_pk_bf16_f32 v45, v42, v43
	global_store_dwordx2 v[12:13], v[44:45], off offset:3072
	v_pk_mul_f32 v[36:37], v[26:27], v[2:3] op_sel_hi:[1,0]
	v_pk_mul_f32 v[38:39], v[32:33], v[2:3] op_sel_hi:[1,0]
	s_waitcnt vmcnt(3)
	v_pk_fma_f32 v[40:41], v[228:229], v[36:37], v[244:245]
	v_pk_fma_f32 v[42:43], v[230:231], v[38:39], v[246:247]
	v_cvt_pk_bf16_f32 v46, v40, v41
	v_cvt_pk_bf16_f32 v47, v42, v43
	global_store_dwordx2 v[12:13], v[46:47], off offset:3584
	s_cbranch_scc0 .LBB0_555
